# prep compress_item: k loop unrolled into 8 rounds with two register buffers, 24 loads per round in flight and counted vmcnt waits
# speedup vs baseline: 1.0094x; 1.0022x over previous
; #define MFMA16(a, b, c) __builtin_amdgcn_mfma_f32_16x16x32_bf16((a), (b), (c), 0, 0, 0)
; DI void compress_item(const Args& a, int l, int item, LAS unsigned char* lds) {
;     ...
;     const bf16_t* w1 = W + W_C1 + (size_t)kv * 262144 + (size_t)(wid * 16 + fr) * 2048 + fq * 8;
;     int tk0[2];
; #pragma unroll
;     for (int m = 0; m < 2; ++m) tk0[m] = 16 * (nq * 32 + m * 16 + fr);
; #pragma unroll 1
;     for (int k8 = 0; k8 < 64; k8 += 8) {
;         bf16x8 bfr[8], af[8][2];
; #pragma unroll
;         for (int kk = 0; kk < 8; ++kk) {
;             const int ks = k8 + kk, tokoff = ks >> 1, dcol = (ks & 1) * 32 + fq * 8;
;             bfr[kk] = *(const bf16x8*)(w1 + ks * 32);
; #pragma unroll
;             for (int m = 0; m < 2; ++m) { int tk = tk0[m] + tokoff; tk = tk > SEQ - 1 ? SEQ - 1 : tk; af[kk][m] = *(const bf16x8*)(PROJ + ((size_t)b * SEQ + tk) * PP + colbase + dcol); }
;         }
; #pragma unroll
;         for (int kk = 0; kk < 8; ++kk)
; #pragma unroll
;             for (int m = 0; m < 2; ++m) acc[m] = MFMA16(af[kk][m], bfr[kk], acc[m]);
.LBB0_604:
	v_lshl_add_u64 v[208:209], v[18:19], 0, v[12:13]
	v_lshl_add_u64 v[252:253], v[16:17], 0, v[12:13]
	global_load_dwordx4 v[24:27], v[208:209], off offset:-256
	s_mov_b64 s[14:15], 0x2400000
	v_lshl_add_u64 v[254:255], v[252:253], 0, s[14:15]
	global_load_dwordx4 v[56:59], v[254:255], off
	global_load_dwordx4 v[28:31], v[208:209], off offset:-192
	global_load_dwordx4 v[60:63], v[254:255], off offset:64
	v_add_u32_e32 v251, -3, v22
	v_min_u32_e32 v251, 0xfff, v251
	v_or_b32_e32 v251, s6, v251
	v_mul_u32_u24_e32 v128, 0x1830, v251
	v_lshl_add_u64 v[254:255], v[14:15], 0, v[128:129]
	global_load_dwordx4 v[88:91], v[254:255], off
	global_load_dwordx4 v[92:95], v[254:255], off offset:64
	global_load_dwordx4 v[32:35], v[208:209], off offset:-128
	s_mov_b64 s[14:15], 0x2401830
	v_lshl_add_u64 v[254:255], v[252:253], 0, s[14:15]
	global_load_dwordx4 v[64:67], v[254:255], off
	global_load_dwordx4 v[36:39], v[208:209], off offset:-64
	global_load_dwordx4 v[68:71], v[254:255], off offset:64
	v_add_u32_e32 v251, -2, v22
	v_min_u32_e32 v251, 0xfff, v251
	v_or_b32_e32 v251, s6, v251
	v_mul_u32_u24_e32 v128, 0x1830, v251
	v_lshl_add_u64 v[254:255], v[14:15], 0, v[128:129]
	global_load_dwordx4 v[96:99], v[254:255], off
	global_load_dwordx4 v[100:103], v[254:255], off offset:64
	global_load_dwordx4 v[40:43], v[208:209], off
	s_mov_b64 s[14:15], 0x2403060
	v_lshl_add_u64 v[254:255], v[252:253], 0, s[14:15]
	global_load_dwordx4 v[72:75], v[254:255], off
	global_load_dwordx4 v[44:47], v[208:209], off offset:64
	global_load_dwordx4 v[76:79], v[254:255], off offset:64
	v_add_u32_e32 v251, -1, v22
	v_min_u32_e32 v251, 0xfff, v251
	v_or_b32_e32 v251, s6, v251
	v_mul_u32_u24_e32 v128, 0x1830, v251
	v_lshl_add_u64 v[254:255], v[14:15], 0, v[128:129]
	global_load_dwordx4 v[104:107], v[254:255], off
	global_load_dwordx4 v[108:111], v[254:255], off offset:64
	global_load_dwordx4 v[48:51], v[208:209], off offset:128
	s_mov_b64 s[14:15], 0x2404890
	v_lshl_add_u64 v[254:255], v[252:253], 0, s[14:15]
	global_load_dwordx4 v[80:83], v[254:255], off
	global_load_dwordx4 v[52:55], v[208:209], off offset:192
	global_load_dwordx4 v[84:87], v[254:255], off offset:64
	v_add_u32_e32 v251, 0, v22
	v_min_u32_e32 v251, 0xfff, v251
	v_or_b32_e32 v251, s6, v251
	v_mul_u32_u24_e32 v128, 0x1830, v251
	v_lshl_add_u64 v[254:255], v[14:15], 0, v[128:129]
	global_load_dwordx4 v[112:115], v[254:255], off
	global_load_dwordx4 v[116:119], v[254:255], off offset:64
	global_load_dwordx4 v[130:133], v[208:209], off offset:256
	s_mov_b64 s[14:15], 0x24060c0
	v_lshl_add_u64 v[254:255], v[252:253], 0, s[14:15]
	global_load_dwordx4 v[176:179], v[254:255], off
	global_load_dwordx4 v[134:137], v[208:209], off offset:320
	global_load_dwordx4 v[180:183], v[254:255], off offset:64
	v_add_u32_e32 v251, 1, v22
	v_min_u32_e32 v251, 0xfff, v251
	v_or_b32_e32 v251, s6, v251
	v_mul_u32_u24_e32 v128, 0x1830, v251
	v_lshl_add_u64 v[254:255], v[14:15], 0, v[128:129]
	global_load_dwordx4 v[220:223], v[254:255], off
	global_load_dwordx4 v[224:227], v[254:255], off offset:64
	global_load_dwordx4 v[138:141], v[208:209], off offset:384
	s_mov_b64 s[14:15], 0x24078f0
	v_lshl_add_u64 v[254:255], v[252:253], 0, s[14:15]
	global_load_dwordx4 v[184:187], v[254:255], off
	global_load_dwordx4 v[142:145], v[208:209], off offset:448
	global_load_dwordx4 v[196:199], v[254:255], off offset:64
	v_add_u32_e32 v251, 2, v22
	v_min_u32_e32 v251, 0xfff, v251
	v_or_b32_e32 v251, s6, v251
	v_mul_u32_u24_e32 v128, 0x1830, v251
	v_lshl_add_u64 v[254:255], v[14:15], 0, v[128:129]
	global_load_dwordx4 v[228:231], v[254:255], off
	global_load_dwordx4 v[232:235], v[254:255], off offset:64
	global_load_dwordx4 v[146:149], v[208:209], off offset:512
	s_mov_b64 s[14:15], 0x2409120
	v_lshl_add_u64 v[254:255], v[252:253], 0, s[14:15]
	global_load_dwordx4 v[200:203], v[254:255], off
	global_load_dwordx4 v[150:153], v[208:209], off offset:576
	global_load_dwordx4 v[204:207], v[254:255], off offset:64
	v_add_u32_e32 v251, 3, v22
	v_min_u32_e32 v251, 0xfff, v251
	v_or_b32_e32 v251, s6, v251
	v_mul_u32_u24_e32 v128, 0x1830, v251
	v_lshl_add_u64 v[254:255], v[14:15], 0, v[128:129]
	global_load_dwordx4 v[236:239], v[254:255], off
	global_load_dwordx4 v[240:243], v[254:255], off offset:64
	global_load_dwordx4 v[168:171], v[208:209], off offset:640
	s_mov_b64 s[14:15], 0x240a950
	v_lshl_add_u64 v[254:255], v[252:253], 0, s[14:15]
	global_load_dwordx4 v[212:215], v[254:255], off
	global_load_dwordx4 v[172:175], v[208:209], off offset:704
	global_load_dwordx4 v[216:219], v[254:255], off offset:64
	v_add_u32_e32 v251, 4, v22
	v_min_u32_e32 v251, 0xfff, v251
	v_or_b32_e32 v251, s6, v251
	v_mul_u32_u24_e32 v128, 0x1830, v251
	v_lshl_add_u64 v[254:255], v[14:15], 0, v[128:129]
	global_load_dwordx4 v[120:123], v[254:255], off
	global_load_dwordx4 v[124:127], v[254:255], off offset:64
	s_waitcnt vmcnt(46)
	v_mfma_f32_16x16x32_bf16 v[4:7], v[56:59], v[24:27], v[4:7]
	s_waitcnt vmcnt(43)
	v_mfma_f32_16x16x32_bf16 v[0:3], v[88:91], v[24:27], v[0:3]
	s_waitcnt vmcnt(44)
	v_mfma_f32_16x16x32_bf16 v[4:7], v[60:63], v[28:31], v[4:7]
	s_waitcnt vmcnt(42)
	v_mfma_f32_16x16x32_bf16 v[0:3], v[92:95], v[28:31], v[0:3]
	s_waitcnt vmcnt(40)
	v_mfma_f32_16x16x32_bf16 v[4:7], v[64:67], v[32:35], v[4:7]
	s_waitcnt vmcnt(37)
	v_mfma_f32_16x16x32_bf16 v[0:3], v[96:99], v[32:35], v[0:3]
	s_waitcnt vmcnt(38)
	v_mfma_f32_16x16x32_bf16 v[4:7], v[68:71], v[36:39], v[4:7]
	s_waitcnt vmcnt(36)
	v_mfma_f32_16x16x32_bf16 v[0:3], v[100:103], v[36:39], v[0:3]
	s_waitcnt vmcnt(34)
	v_mfma_f32_16x16x32_bf16 v[4:7], v[72:75], v[40:43], v[4:7]
	s_waitcnt vmcnt(31)
; #define MFMA16(a, b, c) __builtin_amdgcn_mfma_f32_16x16x32_bf16((a), (b), (c), 0, 0, 0)
; DI void compress_item(const Args& a, int l, int item, LAS unsigned char* lds) {
;     ...
; #pragma unroll 1
;     for (int k8 = 0; k8 < 64; k8 += 8) {
;         bf16x8 bfr[8], af[8][2];
; #pragma unroll
;         for (int kk = 0; kk < 8; ++kk) {
;             const int ks = k8 + kk, tokoff = ks >> 1, dcol = (ks & 1) * 32 + fq * 8;
;             bfr[kk] = *(const bf16x8*)(w1 + ks * 32);
; #pragma unroll
;             for (int m = 0; m < 2; ++m) { int tk = tk0[m] + tokoff; tk = tk > SEQ - 1 ? SEQ - 1 : tk; af[kk][m] = *(const bf16x8*)(PROJ + ((size_t)b * SEQ + tk) * PP + colbase + dcol); }
;         }
; #pragma unroll
;         for (int kk = 0; kk < 8; ++kk)
; #pragma unroll
;             for (int m = 0; m < 2; ++m) acc[m] = MFMA16(af[kk][m], bfr[kk], acc[m]);
	v_mfma_f32_16x16x32_bf16 v[0:3], v[104:107], v[40:43], v[0:3]
	s_waitcnt vmcnt(32)
	v_mfma_f32_16x16x32_bf16 v[4:7], v[76:79], v[44:47], v[4:7]
	s_waitcnt vmcnt(30)
	v_mfma_f32_16x16x32_bf16 v[0:3], v[108:111], v[44:47], v[0:3]
	s_waitcnt vmcnt(28)
	v_mfma_f32_16x16x32_bf16 v[4:7], v[80:83], v[48:51], v[4:7]
	s_waitcnt vmcnt(25)
	v_mfma_f32_16x16x32_bf16 v[0:3], v[112:115], v[48:51], v[0:3]
	s_waitcnt vmcnt(26)
	v_mfma_f32_16x16x32_bf16 v[4:7], v[84:87], v[52:55], v[4:7]
	s_waitcnt vmcnt(24)
	v_mfma_f32_16x16x32_bf16 v[0:3], v[116:119], v[52:55], v[0:3]
	global_load_dwordx4 v[24:27], v[208:209], off offset:768
	s_mov_b64 s[14:15], 0x240c180
	v_lshl_add_u64 v[254:255], v[252:253], 0, s[14:15]
	global_load_dwordx4 v[56:59], v[254:255], off
	global_load_dwordx4 v[28:31], v[208:209], off offset:832
	global_load_dwordx4 v[60:63], v[254:255], off offset:64
	v_add_u32_e32 v251, 5, v22
	v_min_u32_e32 v251, 0xfff, v251
	v_or_b32_e32 v251, s6, v251
	v_mul_u32_u24_e32 v128, 0x1830, v251
	v_lshl_add_u64 v[254:255], v[14:15], 0, v[128:129]
	global_load_dwordx4 v[88:91], v[254:255], off
	global_load_dwordx4 v[92:95], v[254:255], off offset:64
	global_load_dwordx4 v[32:35], v[208:209], off offset:896
	s_mov_b64 s[14:15], 0x240d9b0
	v_lshl_add_u64 v[254:255], v[252:253], 0, s[14:15]
	global_load_dwordx4 v[64:67], v[254:255], off
	global_load_dwordx4 v[36:39], v[208:209], off offset:960
	global_load_dwordx4 v[68:71], v[254:255], off offset:64
	v_add_u32_e32 v251, 6, v22
	v_min_u32_e32 v251, 0xfff, v251
	v_or_b32_e32 v251, s6, v251
	v_mul_u32_u24_e32 v128, 0x1830, v251
	v_lshl_add_u64 v[254:255], v[14:15], 0, v[128:129]
	global_load_dwordx4 v[96:99], v[254:255], off
	global_load_dwordx4 v[100:103], v[254:255], off offset:64
	global_load_dwordx4 v[40:43], v[208:209], off offset:1024
	s_mov_b64 s[14:15], 0x240f1e0
	v_lshl_add_u64 v[254:255], v[252:253], 0, s[14:15]
	global_load_dwordx4 v[72:75], v[254:255], off
	global_load_dwordx4 v[44:47], v[208:209], off offset:1088
	global_load_dwordx4 v[76:79], v[254:255], off offset:64
	v_add_u32_e32 v251, 7, v22
	v_min_u32_e32 v251, 0xfff, v251
	v_or_b32_e32 v251, s6, v251
	v_mul_u32_u24_e32 v128, 0x1830, v251
	v_lshl_add_u64 v[254:255], v[14:15], 0, v[128:129]
	global_load_dwordx4 v[104:107], v[254:255], off
	global_load_dwordx4 v[108:111], v[254:255], off offset:64
	global_load_dwordx4 v[48:51], v[208:209], off offset:1152
	s_mov_b64 s[14:15], 0x2410a10
	v_lshl_add_u64 v[254:255], v[252:253], 0, s[14:15]
	global_load_dwordx4 v[80:83], v[254:255], off
	global_load_dwordx4 v[52:55], v[208:209], off offset:1216
	global_load_dwordx4 v[84:87], v[254:255], off offset:64
	v_add_u32_e32 v251, 8, v22
	v_min_u32_e32 v251, 0xfff, v251
	v_or_b32_e32 v251, s6, v251
	v_mul_u32_u24_e32 v128, 0x1830, v251
	v_lshl_add_u64 v[254:255], v[14:15], 0, v[128:129]
	global_load_dwordx4 v[112:115], v[254:255], off
	global_load_dwordx4 v[116:119], v[254:255], off offset:64
	s_waitcnt vmcnt(46)
	v_mfma_f32_16x16x32_bf16 v[4:7], v[176:179], v[130:133], v[4:7]
	s_waitcnt vmcnt(43)
	v_mfma_f32_16x16x32_bf16 v[0:3], v[220:223], v[130:133], v[0:3]
	s_waitcnt vmcnt(44)
	v_mfma_f32_16x16x32_bf16 v[4:7], v[180:183], v[134:137], v[4:7]
	s_waitcnt vmcnt(42)
	v_mfma_f32_16x16x32_bf16 v[0:3], v[224:227], v[134:137], v[0:3]
	s_waitcnt vmcnt(40)
	v_mfma_f32_16x16x32_bf16 v[4:7], v[184:187], v[138:141], v[4:7]
	s_waitcnt vmcnt(37)
	v_mfma_f32_16x16x32_bf16 v[0:3], v[228:231], v[138:141], v[0:3]
	s_waitcnt vmcnt(38)
	v_mfma_f32_16x16x32_bf16 v[4:7], v[196:199], v[142:145], v[4:7]
	s_waitcnt vmcnt(36)
	v_mfma_f32_16x16x32_bf16 v[0:3], v[232:235], v[142:145], v[0:3]
	s_waitcnt vmcnt(34)
	v_mfma_f32_16x16x32_bf16 v[4:7], v[200:203], v[146:149], v[4:7]
	s_waitcnt vmcnt(31)
	v_mfma_f32_16x16x32_bf16 v[0:3], v[236:239], v[146:149], v[0:3]
	s_waitcnt vmcnt(32)
	v_mfma_f32_16x16x32_bf16 v[4:7], v[204:207], v[150:153], v[4:7]
	s_waitcnt vmcnt(30)
	v_mfma_f32_16x16x32_bf16 v[0:3], v[240:243], v[150:153], v[0:3]
	s_waitcnt vmcnt(28)
	v_mfma_f32_16x16x32_bf16 v[4:7], v[212:215], v[168:171], v[4:7]
	s_waitcnt vmcnt(25)
	v_mfma_f32_16x16x32_bf16 v[0:3], v[120:123], v[168:171], v[0:3]
	s_waitcnt vmcnt(26)
	v_mfma_f32_16x16x32_bf16 v[4:7], v[216:219], v[172:175], v[4:7]
	s_waitcnt vmcnt(24)
	v_mfma_f32_16x16x32_bf16 v[0:3], v[124:127], v[172:175], v[0:3]
	global_load_dwordx4 v[130:133], v[208:209], off offset:1280
	s_mov_b64 s[14:15], 0x2412240
	v_lshl_add_u64 v[254:255], v[252:253], 0, s[14:15]
	global_load_dwordx4 v[176:179], v[254:255], off
	global_load_dwordx4 v[134:137], v[208:209], off offset:1344
	global_load_dwordx4 v[180:183], v[254:255], off offset:64
	v_add_u32_e32 v251, 9, v22
	v_min_u32_e32 v251, 0xfff, v251
	v_or_b32_e32 v251, s6, v251
	v_mul_u32_u24_e32 v128, 0x1830, v251
	v_lshl_add_u64 v[254:255], v[14:15], 0, v[128:129]
	global_load_dwordx4 v[220:223], v[254:255], off
	global_load_dwordx4 v[224:227], v[254:255], off offset:64
	global_load_dwordx4 v[138:141], v[208:209], off offset:1408
	s_mov_b64 s[14:15], 0x2413a70
	v_lshl_add_u64 v[254:255], v[252:253], 0, s[14:15]
	global_load_dwordx4 v[184:187], v[254:255], off
	global_load_dwordx4 v[142:145], v[208:209], off offset:1472
	global_load_dwordx4 v[196:199], v[254:255], off offset:64
	v_add_u32_e32 v251, 10, v22
	v_min_u32_e32 v251, 0xfff, v251
	v_or_b32_e32 v251, s6, v251
	v_mul_u32_u24_e32 v128, 0x1830, v251
	v_lshl_add_u64 v[254:255], v[14:15], 0, v[128:129]
	global_load_dwordx4 v[228:231], v[254:255], off
	global_load_dwordx4 v[232:235], v[254:255], off offset:64
	global_load_dwordx4 v[146:149], v[208:209], off offset:1536
	s_mov_b64 s[14:15], 0x24152a0
	v_lshl_add_u64 v[254:255], v[252:253], 0, s[14:15]
	global_load_dwordx4 v[200:203], v[254:255], off
	global_load_dwordx4 v[150:153], v[208:209], off offset:1600
	global_load_dwordx4 v[204:207], v[254:255], off offset:64
	v_add_u32_e32 v251, 11, v22
	v_min_u32_e32 v251, 0xfff, v251
	v_or_b32_e32 v251, s6, v251
	v_mul_u32_u24_e32 v128, 0x1830, v251
	v_lshl_add_u64 v[254:255], v[14:15], 0, v[128:129]
	global_load_dwordx4 v[236:239], v[254:255], off
	global_load_dwordx4 v[240:243], v[254:255], off offset:64
	global_load_dwordx4 v[168:171], v[208:209], off offset:1664
	s_mov_b64 s[14:15], 0x2416ad0
	v_lshl_add_u64 v[254:255], v[252:253], 0, s[14:15]
	global_load_dwordx4 v[212:215], v[254:255], off
	global_load_dwordx4 v[172:175], v[208:209], off offset:1728
	global_load_dwordx4 v[216:219], v[254:255], off offset:64
	v_add_u32_e32 v251, 12, v22
	v_min_u32_e32 v251, 0xfff, v251
	v_or_b32_e32 v251, s6, v251
	v_mul_u32_u24_e32 v128, 0x1830, v251
	v_lshl_add_u64 v[254:255], v[14:15], 0, v[128:129]
	global_load_dwordx4 v[120:123], v[254:255], off
	global_load_dwordx4 v[124:127], v[254:255], off offset:64
	s_waitcnt vmcnt(46)
; #define MFMA16(a, b, c) __builtin_amdgcn_mfma_f32_16x16x32_bf16((a), (b), (c), 0, 0, 0)
; DI void compress_item(const Args& a, int l, int item, LAS unsigned char* lds) {
;     ...
; #pragma unroll 1
;     for (int k8 = 0; k8 < 64; k8 += 8) {
;         bf16x8 bfr[8], af[8][2];
; #pragma unroll
;         for (int kk = 0; kk < 8; ++kk) {
;             const int ks = k8 + kk, tokoff = ks >> 1, dcol = (ks & 1) * 32 + fq * 8;
;             bfr[kk] = *(const bf16x8*)(w1 + ks * 32);
; #pragma unroll
;             for (int m = 0; m < 2; ++m) { int tk = tk0[m] + tokoff; tk = tk > SEQ - 1 ? SEQ - 1 : tk; af[kk][m] = *(const bf16x8*)(PROJ + ((size_t)b * SEQ + tk) * PP + colbase + dcol); }
;         }
; #pragma unroll
;         for (int kk = 0; kk < 8; ++kk)
; #pragma unroll
;             for (int m = 0; m < 2; ++m) acc[m] = MFMA16(af[kk][m], bfr[kk], acc[m]);
	v_mfma_f32_16x16x32_bf16 v[4:7], v[56:59], v[24:27], v[4:7]
	s_waitcnt vmcnt(43)
	v_mfma_f32_16x16x32_bf16 v[0:3], v[88:91], v[24:27], v[0:3]
	s_waitcnt vmcnt(44)
	v_mfma_f32_16x16x32_bf16 v[4:7], v[60:63], v[28:31], v[4:7]
	s_waitcnt vmcnt(42)
	v_mfma_f32_16x16x32_bf16 v[0:3], v[92:95], v[28:31], v[0:3]
	s_waitcnt vmcnt(40)
	v_mfma_f32_16x16x32_bf16 v[4:7], v[64:67], v[32:35], v[4:7]
	s_waitcnt vmcnt(37)
	v_mfma_f32_16x16x32_bf16 v[0:3], v[96:99], v[32:35], v[0:3]
	s_waitcnt vmcnt(38)
	v_mfma_f32_16x16x32_bf16 v[4:7], v[68:71], v[36:39], v[4:7]
	s_waitcnt vmcnt(36)
	v_mfma_f32_16x16x32_bf16 v[0:3], v[100:103], v[36:39], v[0:3]
	s_waitcnt vmcnt(34)
	v_mfma_f32_16x16x32_bf16 v[4:7], v[72:75], v[40:43], v[4:7]
	s_waitcnt vmcnt(31)
	v_mfma_f32_16x16x32_bf16 v[0:3], v[104:107], v[40:43], v[0:3]
	s_waitcnt vmcnt(32)
	v_mfma_f32_16x16x32_bf16 v[4:7], v[76:79], v[44:47], v[4:7]
	s_waitcnt vmcnt(30)
	v_mfma_f32_16x16x32_bf16 v[0:3], v[108:111], v[44:47], v[0:3]
	s_waitcnt vmcnt(28)
	v_mfma_f32_16x16x32_bf16 v[4:7], v[80:83], v[48:51], v[4:7]
	s_waitcnt vmcnt(25)
	v_mfma_f32_16x16x32_bf16 v[0:3], v[112:115], v[48:51], v[0:3]
	s_waitcnt vmcnt(26)
	v_mfma_f32_16x16x32_bf16 v[4:7], v[84:87], v[52:55], v[4:7]
	s_waitcnt vmcnt(24)
	v_mfma_f32_16x16x32_bf16 v[0:3], v[116:119], v[52:55], v[0:3]
	global_load_dwordx4 v[24:27], v[208:209], off offset:1792
	s_mov_b64 s[14:15], 0x2418300
	v_lshl_add_u64 v[254:255], v[252:253], 0, s[14:15]
	global_load_dwordx4 v[56:59], v[254:255], off
	global_load_dwordx4 v[28:31], v[208:209], off offset:1856
	global_load_dwordx4 v[60:63], v[254:255], off offset:64
	v_add_u32_e32 v251, 13, v22
	v_min_u32_e32 v251, 0xfff, v251
	v_or_b32_e32 v251, s6, v251
	v_mul_u32_u24_e32 v128, 0x1830, v251
	v_lshl_add_u64 v[254:255], v[14:15], 0, v[128:129]
	global_load_dwordx4 v[88:91], v[254:255], off
	global_load_dwordx4 v[92:95], v[254:255], off offset:64
	global_load_dwordx4 v[32:35], v[208:209], off offset:1920
	s_mov_b64 s[14:15], 0x2419b30
	v_lshl_add_u64 v[254:255], v[252:253], 0, s[14:15]
	global_load_dwordx4 v[64:67], v[254:255], off
	global_load_dwordx4 v[36:39], v[208:209], off offset:1984
	global_load_dwordx4 v[68:71], v[254:255], off offset:64
	v_add_u32_e32 v251, 14, v22
	v_min_u32_e32 v251, 0xfff, v251
	v_or_b32_e32 v251, s6, v251
	v_mul_u32_u24_e32 v128, 0x1830, v251
	v_lshl_add_u64 v[254:255], v[14:15], 0, v[128:129]
	global_load_dwordx4 v[96:99], v[254:255], off
	global_load_dwordx4 v[100:103], v[254:255], off offset:64
	global_load_dwordx4 v[40:43], v[208:209], off offset:2048
	s_mov_b64 s[14:15], 0x241b360
	v_lshl_add_u64 v[254:255], v[252:253], 0, s[14:15]
	global_load_dwordx4 v[72:75], v[254:255], off
	global_load_dwordx4 v[44:47], v[208:209], off offset:2112
	global_load_dwordx4 v[76:79], v[254:255], off offset:64
	v_add_u32_e32 v251, 15, v22
	v_min_u32_e32 v251, 0xfff, v251
	v_or_b32_e32 v251, s6, v251
	v_mul_u32_u24_e32 v128, 0x1830, v251
	v_lshl_add_u64 v[254:255], v[14:15], 0, v[128:129]
	global_load_dwordx4 v[104:107], v[254:255], off
	global_load_dwordx4 v[108:111], v[254:255], off offset:64
	global_load_dwordx4 v[48:51], v[208:209], off offset:2176
	s_mov_b64 s[14:15], 0x241cb90
	v_lshl_add_u64 v[254:255], v[252:253], 0, s[14:15]
	global_load_dwordx4 v[80:83], v[254:255], off
	global_load_dwordx4 v[52:55], v[208:209], off offset:2240
	global_load_dwordx4 v[84:87], v[254:255], off offset:64
	v_add_u32_e32 v251, 16, v22
	v_min_u32_e32 v251, 0xfff, v251
	v_or_b32_e32 v251, s6, v251
	v_mul_u32_u24_e32 v128, 0x1830, v251
	v_lshl_add_u64 v[254:255], v[14:15], 0, v[128:129]
	global_load_dwordx4 v[112:115], v[254:255], off
	global_load_dwordx4 v[116:119], v[254:255], off offset:64
	s_waitcnt vmcnt(46)
	v_mfma_f32_16x16x32_bf16 v[4:7], v[176:179], v[130:133], v[4:7]
	s_waitcnt vmcnt(43)
	v_mfma_f32_16x16x32_bf16 v[0:3], v[220:223], v[130:133], v[0:3]
	s_waitcnt vmcnt(44)
	v_mfma_f32_16x16x32_bf16 v[4:7], v[180:183], v[134:137], v[4:7]
	s_waitcnt vmcnt(42)
	v_mfma_f32_16x16x32_bf16 v[0:3], v[224:227], v[134:137], v[0:3]
	s_waitcnt vmcnt(40)
	v_mfma_f32_16x16x32_bf16 v[4:7], v[184:187], v[138:141], v[4:7]
	s_waitcnt vmcnt(37)
	v_mfma_f32_16x16x32_bf16 v[0:3], v[228:231], v[138:141], v[0:3]
	s_waitcnt vmcnt(38)
	v_mfma_f32_16x16x32_bf16 v[4:7], v[196:199], v[142:145], v[4:7]
	s_waitcnt vmcnt(36)
	v_mfma_f32_16x16x32_bf16 v[0:3], v[232:235], v[142:145], v[0:3]
	s_waitcnt vmcnt(34)
	v_mfma_f32_16x16x32_bf16 v[4:7], v[200:203], v[146:149], v[4:7]
	s_waitcnt vmcnt(31)
	v_mfma_f32_16x16x32_bf16 v[0:3], v[236:239], v[146:149], v[0:3]
	s_waitcnt vmcnt(32)
	v_mfma_f32_16x16x32_bf16 v[4:7], v[204:207], v[150:153], v[4:7]
	s_waitcnt vmcnt(30)
	v_mfma_f32_16x16x32_bf16 v[0:3], v[240:243], v[150:153], v[0:3]
	s_waitcnt vmcnt(28)
	v_mfma_f32_16x16x32_bf16 v[4:7], v[212:215], v[168:171], v[4:7]
	s_waitcnt vmcnt(25)
	v_mfma_f32_16x16x32_bf16 v[0:3], v[120:123], v[168:171], v[0:3]
	s_waitcnt vmcnt(26)
	v_mfma_f32_16x16x32_bf16 v[4:7], v[216:219], v[172:175], v[4:7]
	s_waitcnt vmcnt(24)
; #define MFMA16(a, b, c) __builtin_amdgcn_mfma_f32_16x16x32_bf16((a), (b), (c), 0, 0, 0)
; DI void compress_item(const Args& a, int l, int item, LAS unsigned char* lds) {
;     ...
; #pragma unroll 1
;     for (int k8 = 0; k8 < 64; k8 += 8) {
;         bf16x8 bfr[8], af[8][2];
; #pragma unroll
;         for (int kk = 0; kk < 8; ++kk) {
;             const int ks = k8 + kk, tokoff = ks >> 1, dcol = (ks & 1) * 32 + fq * 8;
;             bfr[kk] = *(const bf16x8*)(w1 + ks * 32);
; #pragma unroll
;             for (int m = 0; m < 2; ++m) { int tk = tk0[m] + tokoff; tk = tk > SEQ - 1 ? SEQ - 1 : tk; af[kk][m] = *(const bf16x8*)(PROJ + ((size_t)b * SEQ + tk) * PP + colbase + dcol); }
;         }
; #pragma unroll
;         for (int kk = 0; kk < 8; ++kk)
; #pragma unroll
;             for (int m = 0; m < 2; ++m) acc[m] = MFMA16(af[kk][m], bfr[kk], acc[m]);
	v_mfma_f32_16x16x32_bf16 v[0:3], v[124:127], v[172:175], v[0:3]
	global_load_dwordx4 v[130:133], v[208:209], off offset:2304
	s_mov_b64 s[14:15], 0x241e3c0
	v_lshl_add_u64 v[254:255], v[252:253], 0, s[14:15]
	global_load_dwordx4 v[176:179], v[254:255], off
	global_load_dwordx4 v[134:137], v[208:209], off offset:2368
	global_load_dwordx4 v[180:183], v[254:255], off offset:64
	v_add_u32_e32 v251, 17, v22
	v_min_u32_e32 v251, 0xfff, v251
	v_or_b32_e32 v251, s6, v251
	v_mul_u32_u24_e32 v128, 0x1830, v251
	v_lshl_add_u64 v[254:255], v[14:15], 0, v[128:129]
	global_load_dwordx4 v[220:223], v[254:255], off
	global_load_dwordx4 v[224:227], v[254:255], off offset:64
	global_load_dwordx4 v[138:141], v[208:209], off offset:2432
	s_mov_b64 s[14:15], 0x241fbf0
	v_lshl_add_u64 v[254:255], v[252:253], 0, s[14:15]
	global_load_dwordx4 v[184:187], v[254:255], off
	global_load_dwordx4 v[142:145], v[208:209], off offset:2496
	global_load_dwordx4 v[196:199], v[254:255], off offset:64
	v_add_u32_e32 v251, 18, v22
	v_min_u32_e32 v251, 0xfff, v251
	v_or_b32_e32 v251, s6, v251
	v_mul_u32_u24_e32 v128, 0x1830, v251
	v_lshl_add_u64 v[254:255], v[14:15], 0, v[128:129]
	global_load_dwordx4 v[228:231], v[254:255], off
	global_load_dwordx4 v[232:235], v[254:255], off offset:64
	global_load_dwordx4 v[146:149], v[208:209], off offset:2560
	s_mov_b64 s[14:15], 0x2421420
	v_lshl_add_u64 v[254:255], v[252:253], 0, s[14:15]
	global_load_dwordx4 v[200:203], v[254:255], off
	global_load_dwordx4 v[150:153], v[208:209], off offset:2624
	global_load_dwordx4 v[204:207], v[254:255], off offset:64
	v_add_u32_e32 v251, 19, v22
	v_min_u32_e32 v251, 0xfff, v251
	v_or_b32_e32 v251, s6, v251
	v_mul_u32_u24_e32 v128, 0x1830, v251
	v_lshl_add_u64 v[254:255], v[14:15], 0, v[128:129]
	global_load_dwordx4 v[236:239], v[254:255], off
	global_load_dwordx4 v[240:243], v[254:255], off offset:64
	global_load_dwordx4 v[168:171], v[208:209], off offset:2688
	s_mov_b64 s[14:15], 0x2422c50
	v_lshl_add_u64 v[254:255], v[252:253], 0, s[14:15]
	global_load_dwordx4 v[212:215], v[254:255], off
	global_load_dwordx4 v[172:175], v[208:209], off offset:2752
	global_load_dwordx4 v[216:219], v[254:255], off offset:64
	v_add_u32_e32 v251, 20, v22
	v_min_u32_e32 v251, 0xfff, v251
	v_or_b32_e32 v251, s6, v251
	v_mul_u32_u24_e32 v128, 0x1830, v251
	v_lshl_add_u64 v[254:255], v[14:15], 0, v[128:129]
	global_load_dwordx4 v[120:123], v[254:255], off
	global_load_dwordx4 v[124:127], v[254:255], off offset:64
	s_waitcnt vmcnt(46)
	v_mfma_f32_16x16x32_bf16 v[4:7], v[56:59], v[24:27], v[4:7]
	s_waitcnt vmcnt(43)
	v_mfma_f32_16x16x32_bf16 v[0:3], v[88:91], v[24:27], v[0:3]
	s_waitcnt vmcnt(44)
	v_mfma_f32_16x16x32_bf16 v[4:7], v[60:63], v[28:31], v[4:7]
	s_waitcnt vmcnt(42)
	v_mfma_f32_16x16x32_bf16 v[0:3], v[92:95], v[28:31], v[0:3]
	s_waitcnt vmcnt(40)
	v_mfma_f32_16x16x32_bf16 v[4:7], v[64:67], v[32:35], v[4:7]
	s_waitcnt vmcnt(37)
	v_mfma_f32_16x16x32_bf16 v[0:3], v[96:99], v[32:35], v[0:3]
	s_waitcnt vmcnt(38)
	v_mfma_f32_16x16x32_bf16 v[4:7], v[68:71], v[36:39], v[4:7]
	s_waitcnt vmcnt(36)
	v_mfma_f32_16x16x32_bf16 v[0:3], v[100:103], v[36:39], v[0:3]
	s_waitcnt vmcnt(34)
	v_mfma_f32_16x16x32_bf16 v[4:7], v[72:75], v[40:43], v[4:7]
	s_waitcnt vmcnt(31)
	v_mfma_f32_16x16x32_bf16 v[0:3], v[104:107], v[40:43], v[0:3]
	s_waitcnt vmcnt(32)
	v_mfma_f32_16x16x32_bf16 v[4:7], v[76:79], v[44:47], v[4:7]
	s_waitcnt vmcnt(30)
	v_mfma_f32_16x16x32_bf16 v[0:3], v[108:111], v[44:47], v[0:3]
	s_waitcnt vmcnt(28)
	v_mfma_f32_16x16x32_bf16 v[4:7], v[80:83], v[48:51], v[4:7]
	s_waitcnt vmcnt(25)
	v_mfma_f32_16x16x32_bf16 v[0:3], v[112:115], v[48:51], v[0:3]
	s_waitcnt vmcnt(26)
	v_mfma_f32_16x16x32_bf16 v[4:7], v[84:87], v[52:55], v[4:7]
	s_waitcnt vmcnt(24)
	v_mfma_f32_16x16x32_bf16 v[0:3], v[116:119], v[52:55], v[0:3]
	global_load_dwordx4 v[24:27], v[208:209], off offset:2816
	s_mov_b64 s[14:15], 0x2424480
	v_lshl_add_u64 v[254:255], v[252:253], 0, s[14:15]
	global_load_dwordx4 v[56:59], v[254:255], off
	global_load_dwordx4 v[28:31], v[208:209], off offset:2880
	global_load_dwordx4 v[60:63], v[254:255], off offset:64
	v_add_u32_e32 v251, 21, v22
	v_min_u32_e32 v251, 0xfff, v251
	v_or_b32_e32 v251, s6, v251
	v_mul_u32_u24_e32 v128, 0x1830, v251
	v_lshl_add_u64 v[254:255], v[14:15], 0, v[128:129]
	global_load_dwordx4 v[88:91], v[254:255], off
	global_load_dwordx4 v[92:95], v[254:255], off offset:64
	global_load_dwordx4 v[32:35], v[208:209], off offset:2944
	s_mov_b64 s[14:15], 0x2425cb0
	v_lshl_add_u64 v[254:255], v[252:253], 0, s[14:15]
	global_load_dwordx4 v[64:67], v[254:255], off
	global_load_dwordx4 v[36:39], v[208:209], off offset:3008
	global_load_dwordx4 v[68:71], v[254:255], off offset:64
	v_add_u32_e32 v251, 22, v22
	v_min_u32_e32 v251, 0xfff, v251
	v_or_b32_e32 v251, s6, v251
	v_mul_u32_u24_e32 v128, 0x1830, v251
	v_lshl_add_u64 v[254:255], v[14:15], 0, v[128:129]
	global_load_dwordx4 v[96:99], v[254:255], off
	global_load_dwordx4 v[100:103], v[254:255], off offset:64
	global_load_dwordx4 v[40:43], v[208:209], off offset:3072
	s_mov_b64 s[14:15], 0x24274e0
	v_lshl_add_u64 v[254:255], v[252:253], 0, s[14:15]
	global_load_dwordx4 v[72:75], v[254:255], off
	global_load_dwordx4 v[44:47], v[208:209], off offset:3136
	global_load_dwordx4 v[76:79], v[254:255], off offset:64
	v_add_u32_e32 v251, 23, v22
	v_min_u32_e32 v251, 0xfff, v251
	v_or_b32_e32 v251, s6, v251
	v_mul_u32_u24_e32 v128, 0x1830, v251
	v_lshl_add_u64 v[254:255], v[14:15], 0, v[128:129]
	global_load_dwordx4 v[104:107], v[254:255], off
	global_load_dwordx4 v[108:111], v[254:255], off offset:64
	global_load_dwordx4 v[48:51], v[208:209], off offset:3200
	s_mov_b64 s[14:15], 0x2428d10
	v_lshl_add_u64 v[254:255], v[252:253], 0, s[14:15]
	global_load_dwordx4 v[80:83], v[254:255], off
	global_load_dwordx4 v[52:55], v[208:209], off offset:3264
	global_load_dwordx4 v[84:87], v[254:255], off offset:64
	v_add_u32_e32 v251, 24, v22
	v_min_u32_e32 v251, 0xfff, v251
	v_or_b32_e32 v251, s6, v251
	v_mul_u32_u24_e32 v128, 0x1830, v251
	v_lshl_add_u64 v[254:255], v[14:15], 0, v[128:129]
	global_load_dwordx4 v[112:115], v[254:255], off
	global_load_dwordx4 v[116:119], v[254:255], off offset:64
	s_waitcnt vmcnt(46)
; #define MFMA16(a, b, c) __builtin_amdgcn_mfma_f32_16x16x32_bf16((a), (b), (c), 0, 0, 0)
; DI void compress_item(const Args& a, int l, int item, LAS unsigned char* lds) {
;     ...
; #pragma unroll 1
;     for (int k8 = 0; k8 < 64; k8 += 8) {
;         bf16x8 bfr[8], af[8][2];
; #pragma unroll
;         for (int kk = 0; kk < 8; ++kk) {
;             const int ks = k8 + kk, tokoff = ks >> 1, dcol = (ks & 1) * 32 + fq * 8;
;             bfr[kk] = *(const bf16x8*)(w1 + ks * 32);
; #pragma unroll
;             for (int m = 0; m < 2; ++m) { int tk = tk0[m] + tokoff; tk = tk > SEQ - 1 ? SEQ - 1 : tk; af[kk][m] = *(const bf16x8*)(PROJ + ((size_t)b * SEQ + tk) * PP + colbase + dcol); }
;         }
; #pragma unroll
;         for (int kk = 0; kk < 8; ++kk)
; #pragma unroll
;             for (int m = 0; m < 2; ++m) acc[m] = MFMA16(af[kk][m], bfr[kk], acc[m]);
	v_mfma_f32_16x16x32_bf16 v[4:7], v[176:179], v[130:133], v[4:7]
	s_waitcnt vmcnt(43)
	v_mfma_f32_16x16x32_bf16 v[0:3], v[220:223], v[130:133], v[0:3]
	s_waitcnt vmcnt(44)
	v_mfma_f32_16x16x32_bf16 v[4:7], v[180:183], v[134:137], v[4:7]
	s_waitcnt vmcnt(42)
	v_mfma_f32_16x16x32_bf16 v[0:3], v[224:227], v[134:137], v[0:3]
	s_waitcnt vmcnt(40)
	v_mfma_f32_16x16x32_bf16 v[4:7], v[184:187], v[138:141], v[4:7]
	s_waitcnt vmcnt(37)
	v_mfma_f32_16x16x32_bf16 v[0:3], v[228:231], v[138:141], v[0:3]
	s_waitcnt vmcnt(38)
	v_mfma_f32_16x16x32_bf16 v[4:7], v[196:199], v[142:145], v[4:7]
	s_waitcnt vmcnt(36)
	v_mfma_f32_16x16x32_bf16 v[0:3], v[232:235], v[142:145], v[0:3]
	s_waitcnt vmcnt(34)
	v_mfma_f32_16x16x32_bf16 v[4:7], v[200:203], v[146:149], v[4:7]
	s_waitcnt vmcnt(31)
	v_mfma_f32_16x16x32_bf16 v[0:3], v[236:239], v[146:149], v[0:3]
	s_waitcnt vmcnt(32)
	v_mfma_f32_16x16x32_bf16 v[4:7], v[204:207], v[150:153], v[4:7]
	s_waitcnt vmcnt(30)
	v_mfma_f32_16x16x32_bf16 v[0:3], v[240:243], v[150:153], v[0:3]
	s_waitcnt vmcnt(28)
	v_mfma_f32_16x16x32_bf16 v[4:7], v[212:215], v[168:171], v[4:7]
	s_waitcnt vmcnt(25)
	v_mfma_f32_16x16x32_bf16 v[0:3], v[120:123], v[168:171], v[0:3]
	s_waitcnt vmcnt(26)
	v_mfma_f32_16x16x32_bf16 v[4:7], v[216:219], v[172:175], v[4:7]
	s_waitcnt vmcnt(24)
	v_mfma_f32_16x16x32_bf16 v[0:3], v[124:127], v[172:175], v[0:3]
	global_load_dwordx4 v[130:133], v[208:209], off offset:3328
	s_mov_b64 s[14:15], 0x242a540
	v_lshl_add_u64 v[254:255], v[252:253], 0, s[14:15]
	global_load_dwordx4 v[176:179], v[254:255], off
	global_load_dwordx4 v[134:137], v[208:209], off offset:3392
	global_load_dwordx4 v[180:183], v[254:255], off offset:64
	v_add_u32_e32 v251, 25, v22
	v_min_u32_e32 v251, 0xfff, v251
	v_or_b32_e32 v251, s6, v251
	v_mul_u32_u24_e32 v128, 0x1830, v251
	v_lshl_add_u64 v[254:255], v[14:15], 0, v[128:129]
	global_load_dwordx4 v[220:223], v[254:255], off
	global_load_dwordx4 v[224:227], v[254:255], off offset:64
	global_load_dwordx4 v[138:141], v[208:209], off offset:3456
	s_mov_b64 s[14:15], 0x242bd70
	v_lshl_add_u64 v[254:255], v[252:253], 0, s[14:15]
	global_load_dwordx4 v[184:187], v[254:255], off
	global_load_dwordx4 v[142:145], v[208:209], off offset:3520
	global_load_dwordx4 v[196:199], v[254:255], off offset:64
	v_add_u32_e32 v251, 26, v22
	v_min_u32_e32 v251, 0xfff, v251
	v_or_b32_e32 v251, s6, v251
	v_mul_u32_u24_e32 v128, 0x1830, v251
	v_lshl_add_u64 v[254:255], v[14:15], 0, v[128:129]
	global_load_dwordx4 v[228:231], v[254:255], off
	global_load_dwordx4 v[232:235], v[254:255], off offset:64
	global_load_dwordx4 v[146:149], v[208:209], off offset:3584
	s_mov_b64 s[14:15], 0x242d5a0
	v_lshl_add_u64 v[254:255], v[252:253], 0, s[14:15]
	global_load_dwordx4 v[200:203], v[254:255], off
	global_load_dwordx4 v[150:153], v[208:209], off offset:3648
	global_load_dwordx4 v[204:207], v[254:255], off offset:64
	v_add_u32_e32 v251, 27, v22
	v_min_u32_e32 v251, 0xfff, v251
	v_or_b32_e32 v251, s6, v251
	v_mul_u32_u24_e32 v128, 0x1830, v251
	v_lshl_add_u64 v[254:255], v[14:15], 0, v[128:129]
	global_load_dwordx4 v[236:239], v[254:255], off
	global_load_dwordx4 v[240:243], v[254:255], off offset:64
	global_load_dwordx4 v[168:171], v[208:209], off offset:3712
	s_mov_b64 s[14:15], 0x242edd0
	v_lshl_add_u64 v[254:255], v[252:253], 0, s[14:15]
	global_load_dwordx4 v[212:215], v[254:255], off
	global_load_dwordx4 v[172:175], v[208:209], off offset:3776
	global_load_dwordx4 v[216:219], v[254:255], off offset:64
	v_add_u32_e32 v251, 28, v22
	v_min_u32_e32 v251, 0xfff, v251
	v_or_b32_e32 v251, s6, v251
	v_mul_u32_u24_e32 v128, 0x1830, v251
	v_lshl_add_u64 v[254:255], v[14:15], 0, v[128:129]
	global_load_dwordx4 v[120:123], v[254:255], off
	global_load_dwordx4 v[124:127], v[254:255], off offset:64
	s_waitcnt vmcnt(46)
	v_mfma_f32_16x16x32_bf16 v[4:7], v[56:59], v[24:27], v[4:7]
	s_waitcnt vmcnt(43)
	v_mfma_f32_16x16x32_bf16 v[0:3], v[88:91], v[24:27], v[0:3]
	s_waitcnt vmcnt(44)
	v_mfma_f32_16x16x32_bf16 v[4:7], v[60:63], v[28:31], v[4:7]
	s_waitcnt vmcnt(42)
	v_mfma_f32_16x16x32_bf16 v[0:3], v[92:95], v[28:31], v[0:3]
	s_waitcnt vmcnt(40)
	v_mfma_f32_16x16x32_bf16 v[4:7], v[64:67], v[32:35], v[4:7]
	s_waitcnt vmcnt(37)
	v_mfma_f32_16x16x32_bf16 v[0:3], v[96:99], v[32:35], v[0:3]
	s_waitcnt vmcnt(38)
	v_mfma_f32_16x16x32_bf16 v[4:7], v[68:71], v[36:39], v[4:7]
	s_waitcnt vmcnt(36)
	v_mfma_f32_16x16x32_bf16 v[0:3], v[100:103], v[36:39], v[0:3]
	s_waitcnt vmcnt(34)
	v_mfma_f32_16x16x32_bf16 v[4:7], v[72:75], v[40:43], v[4:7]
	s_waitcnt vmcnt(31)
	v_mfma_f32_16x16x32_bf16 v[0:3], v[104:107], v[40:43], v[0:3]
	s_waitcnt vmcnt(32)
	v_mfma_f32_16x16x32_bf16 v[4:7], v[76:79], v[44:47], v[4:7]
	s_waitcnt vmcnt(30)
	v_mfma_f32_16x16x32_bf16 v[0:3], v[108:111], v[44:47], v[0:3]
	s_waitcnt vmcnt(28)
	v_mfma_f32_16x16x32_bf16 v[4:7], v[80:83], v[48:51], v[4:7]
	s_waitcnt vmcnt(25)
	v_mfma_f32_16x16x32_bf16 v[0:3], v[112:115], v[48:51], v[0:3]
	s_waitcnt vmcnt(26)
	v_mfma_f32_16x16x32_bf16 v[4:7], v[84:87], v[52:55], v[4:7]
	s_waitcnt vmcnt(24)
	v_mfma_f32_16x16x32_bf16 v[0:3], v[116:119], v[52:55], v[0:3]
	s_waitcnt vmcnt(22)
	v_mfma_f32_16x16x32_bf16 v[4:7], v[176:179], v[130:133], v[4:7]
	s_waitcnt vmcnt(19)
	v_mfma_f32_16x16x32_bf16 v[0:3], v[220:223], v[130:133], v[0:3]
	s_waitcnt vmcnt(20)
	v_mfma_f32_16x16x32_bf16 v[4:7], v[180:183], v[134:137], v[4:7]
	s_waitcnt vmcnt(18)
	v_mfma_f32_16x16x32_bf16 v[0:3], v[224:227], v[134:137], v[0:3]
	s_waitcnt vmcnt(16)
	v_mfma_f32_16x16x32_bf16 v[4:7], v[184:187], v[138:141], v[4:7]
	s_waitcnt vmcnt(13)
	v_mfma_f32_16x16x32_bf16 v[0:3], v[228:231], v[138:141], v[0:3]
	s_waitcnt vmcnt(14)
; #define MFMA16(a, b, c) __builtin_amdgcn_mfma_f32_16x16x32_bf16((a), (b), (c), 0, 0, 0)
; DI void compress_item(const Args& a, int l, int item, LAS unsigned char* lds) {
;     ...
; #pragma unroll
;         for (int kk = 0; kk < 8; ++kk)
; #pragma unroll
;             for (int m = 0; m < 2; ++m) acc[m] = MFMA16(af[kk][m], bfr[kk], acc[m]);
;     }
;     {
;         const int c = wid * 16 + fr; const float* biasp = (const float*)(a.ws + WS_BIASP) + kv * 16 * 128 + c;
;         float bias = 0.f;
; #pragma unroll
;         for (int kp = 0; kp < 16; ++kp) bias += biasp[kp * 128];
	v_mfma_f32_16x16x32_bf16 v[4:7], v[196:199], v[142:145], v[4:7]
	s_waitcnt vmcnt(12)
	v_mfma_f32_16x16x32_bf16 v[0:3], v[232:235], v[142:145], v[0:3]
	s_waitcnt vmcnt(10)
	v_mfma_f32_16x16x32_bf16 v[4:7], v[200:203], v[146:149], v[4:7]
	s_waitcnt vmcnt(7)
	v_mfma_f32_16x16x32_bf16 v[0:3], v[236:239], v[146:149], v[0:3]
	s_waitcnt vmcnt(8)
	v_mfma_f32_16x16x32_bf16 v[4:7], v[204:207], v[150:153], v[4:7]
	s_waitcnt vmcnt(6)
	v_mfma_f32_16x16x32_bf16 v[0:3], v[240:243], v[150:153], v[0:3]
	s_waitcnt vmcnt(4)
	v_mfma_f32_16x16x32_bf16 v[4:7], v[212:215], v[168:171], v[4:7]
	s_waitcnt vmcnt(1)
	v_mfma_f32_16x16x32_bf16 v[0:3], v[120:123], v[168:171], v[0:3]
	s_waitcnt vmcnt(2)
	v_mfma_f32_16x16x32_bf16 v[4:7], v[216:219], v[172:175], v[4:7]
	s_waitcnt vmcnt(0)
	v_mfma_f32_16x16x32_bf16 v[0:3], v[124:127], v[172:175], v[0:3]
	s_lshl_b32 s6, s4, 11
	s_ashr_i32 s7, s6, 31
	s_lshl_b64 s[6:7], s[6:7], 2
	v_readlane_b32 s14, v245, 14
	v_readlane_b32 s15, v245, 15
	s_add_u32 s6, s14, s6
	s_addc_u32 s7, s15, s7
	v_lshl_add_u64 v[12:13], v[10:11], 2, s[6:7]
	global_load_dword v11, v[12:13], off
	global_load_dword v14, v[12:13], off offset:512
	s_movk_i32 s6, 0x1000
	v_lshlrev_b32_e32 v10, 1, v10
	s_lshl_b64 s[4:5], s[4:5], 14
	v_bfe_u32 v16, v9, 6, 2
	s_waitcnt vmcnt(1)
	v_add_f32_e32 v11, 0, v11
	s_waitcnt vmcnt(0)
	v_add_f32_e32 v11, v11, v14
	global_load_dword v14, v[12:13], off offset:1024
	s_waitcnt vmcnt(0)
	v_add_f32_e32 v11, v11, v14
	global_load_dword v14, v[12:13], off offset:1536
	s_waitcnt vmcnt(0)
	v_add_f32_e32 v11, v11, v14
	global_load_dword v14, v[12:13], off offset:2048
	s_waitcnt vmcnt(0)
	v_add_f32_e32 v11, v11, v14
	global_load_dword v14, v[12:13], off offset:2560
	s_waitcnt vmcnt(0)
	v_add_f32_e32 v11, v11, v14
	global_load_dword v14, v[12:13], off offset:3072
	s_waitcnt vmcnt(0)
	v_add_f32_e32 v11, v11, v14
	global_load_dword v14, v[12:13], off offset:3584
	v_add_co_u32_e32 v12, vcc, s6, v12
	s_movk_i32 s6, 0x110
	s_nop 0
	v_addc_co_u32_e32 v13, vcc, 0, v13, vcc
	s_waitcnt vmcnt(0)
	v_add_f32_e32 v11, v11, v14
	global_load_dword v14, v[12:13], off
	s_waitcnt vmcnt(0)
	v_add_f32_e32 v11, v11, v14
	global_load_dword v14, v[12:13], off offset:512
	s_waitcnt vmcnt(0)
	v_add_f32_e32 v11, v11, v14
	global_load_dword v14, v[12:13], off offset:1024
	s_waitcnt vmcnt(0)
	v_add_f32_e32 v11, v11, v14
	global_load_dword v14, v[12:13], off offset:1536
	s_waitcnt vmcnt(0)
	v_add_f32_e32 v11, v11, v14
	global_load_dword v14, v[12:13], off offset:2048
	s_waitcnt vmcnt(0)
	v_add_f32_e32 v11, v11, v14
	global_load_dword v14, v[12:13], off offset:2560
	s_waitcnt vmcnt(0)
	v_add_f32_e32 v11, v11, v14
	global_load_dword v14, v[12:13], off offset:3072
	s_waitcnt vmcnt(0)
	v_add_f32_e32 v11, v11, v14
	global_load_dword v12, v[12:13], off offset:3584
	s_waitcnt vmcnt(0)
; #define LAS __attribute__((address_space(3)))
; DI bf16_t tobf(float x) { return (bf16_t)(pk2(x, 0.f) & 0xffffu); }
; DI u32x4 pack8(const float* f) { u32x4 w; w.x = pk2(f[0], f[1]); w.y = pk2(f[2], f[3]); w.z = pk2(f[4], f[5]); w.w = pk2(f[6], f[7]); return w; }
; DI float red8(float x) { x = red4(x); x = dpp_add<0x141>(x); return x; }
; #define MFMA16(a, b, c) __builtin_amdgcn_mfma_f32_16x16x32_bf16((a), (b), (c), 0, 0, 0)
; DI float gelu_tanh(float x) { const float u = 0.7978845608f * (x + 0.044715f * x * x * x); return 0.5f * x * (1.f + tanh_fast(u)); }
; DI void compress_item(const Args& a, int l, int item, LAS unsigned char* lds) {
;     ...
; #pragma unroll
;         for (int m = 0; m < 2; ++m)
; #pragma unroll
;             for (int r = 0; r < 4; ++r) hs[(m * 16 + fq * 4 + r) * 136 + c] = tobf(gelu_tanh(acc[m][r] + bias));
;     }
;     __syncthreads();
;     {
;         const int m = wid >> 2, nt = wid & 3;
;         f32x4 acc2 = {0.f, 0.f, 0.f, 0.f};
; #pragma unroll
;         for (int ks = 0; ks < 4; ++ks) {
;             const bf16x8 af = *(const LAS bf16x8*)(hs + (m * 16 + fr) * 136 + ks * 32 + fq * 8);
;             const bf16x8 bf = *(const bf16x8*)(W + W_C2 + (size_t)kv * 8192 + (size_t)(nt * 16 + fr) * 128 + ks * 32 + fq * 8);
;             acc2 = MFMA16(af, bf, acc2);
;         }
; #pragma unroll
;         for (int r = 0; r < 4; ++r) os[(m * 16 + fq * 4 + r) * 64 + nt * 16 + fr] = acc2[r];
;     }
;     __syncthreads();
;     if (tid < 256) {
;         const int rowi = tid >> 3, d0 = (tid & 7) * 8, n = nq * 32 + rowi;
;         float v[8];
; #pragma unroll
;         for (int i = 0; i < 8; ++i) v[i] = os[rowi * 64 + d0 + i];
;         if (kv == 0) {
;             float ss = 0.f;
; #pragma unroll
;             for (int i = 0; i < 8; ++i) ss += v[i] * v[i];
;             ss = red8(ss);
;             const float rstd = rsqrtf(ss * (1.f / 64.f) + 1e-6f);
;             const float* gn = a.in[I_KGAIN] + (l * 3 + 0) * 64 + d0;
; #pragma unroll
;             for (int i = 0; i < 8; ++i) v[i] = (n == 255) ? 0.f : v[i] * rstd * gn[i];
;             *(u32x4*)((bf16_t*)(a.ws + WS_KCN) + ((size_t)bg * 256 + n) * 64 + d0) = pack8(v);
;         } else {
;             bf16_t* vct = (bf16_t*)(a.ws + WS_VCT) + (size_t)bg * 64 * 256;
; #pragma unroll
;             for (int i = 0; i < 8; ++i) vct[(d0 + i) * 256 + n] = tobf(n == 255 ? 0.f : v[i]);
	v_add_f32_e32 v11, v11, v12
	v_add_f32_e32 v4, v4, v11
	v_mul_f32_e32 v12, 0x3d372713, v4
	v_mul_f32_e32 v12, v4, v12
	v_fma_f32 v12, v4, v12, v4
	v_mul_f32_e32 v12, 0x3f4c422a, v12
	v_add_f32_e32 v12, v12, v12
	v_mul_f32_e32 v12, 0x3fb8aa3b, v12
	v_exp_f32_e32 v12, v12
	v_mul_f32_e32 v4, 0.5, v4
	v_add_f32_e32 v5, v5, v11
	v_add_f32_e32 v0, v0, v11
	v_add_f32_e32 v12, 1.0, v12
	v_rcp_f32_e32 v12, v12
	s_nop 0
	v_fma_f32 v12, v12, -2.0, 1.0
	v_add_f32_e32 v12, 1.0, v12
	v_mul_f32_e32 v4, v4, v12
	v_cvt_pk_bf16_f32 v12, v4, s0
	v_mul_u32_u24_e32 v4, 0x440, v20
	v_add3_u32 v4, 0, v10, v4
	v_mul_f32_e32 v10, 0x3d372713, v5
	v_mul_f32_e32 v10, v5, v10
	v_fma_f32 v10, v5, v10, v5
	v_mul_f32_e32 v10, 0x3f4c422a, v10
	v_add_f32_e32 v10, v10, v10
	v_mul_f32_e32 v10, 0x3fb8aa3b, v10
	v_exp_f32_e32 v10, v10
	v_mul_f32_e32 v5, 0.5, v5
	ds_write_b16 v4, v12
	v_add_f32_e32 v10, 1.0, v10
	v_rcp_f32_e32 v10, v10
	s_nop 0
	v_fma_f32 v10, v10, -2.0, 1.0
	v_add_f32_e32 v10, 1.0, v10
	v_mul_f32_e32 v5, v5, v10
	v_cvt_pk_bf16_f32 v5, v5, s0
	ds_write_b16 v4, v5 offset:272
	v_add_f32_e32 v5, v6, v11
	v_mul_f32_e32 v6, 0x3d372713, v5
	v_mul_f32_e32 v6, v5, v6
	v_fma_f32 v6, v5, v6, v5
	v_mul_f32_e32 v6, 0x3f4c422a, v6
	v_add_f32_e32 v6, v6, v6
	v_mul_f32_e32 v6, 0x3fb8aa3b, v6
	v_exp_f32_e32 v6, v6
	v_mul_f32_e32 v5, 0.5, v5
	v_add_f32_e32 v6, 1.0, v6
	v_rcp_f32_e32 v6, v6
	s_nop 0
	v_fma_f32 v6, v6, -2.0, 1.0
	v_add_f32_e32 v6, 1.0, v6
	v_mul_f32_e32 v5, v5, v6
	v_cvt_pk_bf16_f32 v5, v5, s0
	ds_write_b16 v4, v5 offset:544
	v_add_f32_e32 v5, v7, v11
	v_mul_f32_e32 v6, 0x3d372713, v5
	v_mul_f32_e32 v6, v5, v6
	v_fma_f32 v6, v5, v6, v5
	v_mul_f32_e32 v6, 0x3f4c422a, v6
	v_add_f32_e32 v6, v6, v6
	v_mul_f32_e32 v6, 0x3fb8aa3b, v6
	v_exp_f32_e32 v6, v6
	v_mul_f32_e32 v5, 0.5, v5
	v_add_f32_e32 v6, 1.0, v6
	v_rcp_f32_e32 v6, v6
	s_nop 0
	v_fma_f32 v6, v6, -2.0, 1.0
	v_add_f32_e32 v6, 1.0, v6
	v_mul_f32_e32 v5, v5, v6
	v_cvt_pk_bf16_f32 v5, v5, s0
	ds_write_b16 v4, v5 offset:816
	v_mul_f32_e32 v5, 0x3d372713, v0
	v_mul_f32_e32 v5, v0, v5
	v_fma_f32 v5, v0, v5, v0
	v_mul_f32_e32 v5, 0x3f4c422a, v5
	v_add_f32_e32 v5, v5, v5
	v_mul_f32_e32 v5, 0x3fb8aa3b, v5
	v_exp_f32_e32 v5, v5
	v_mul_f32_e32 v0, 0.5, v0
	v_add_f32_e32 v5, 1.0, v5
	v_rcp_f32_e32 v5, v5
	s_nop 0
	v_fma_f32 v5, v5, -2.0, 1.0
	v_add_f32_e32 v5, 1.0, v5
	v_mul_f32_e32 v0, v0, v5
	v_cvt_pk_bf16_f32 v0, v0, s0
	ds_write_b16 v4, v0 offset:4352
	v_add_f32_e32 v0, v1, v11
	v_mul_f32_e32 v1, 0x3d372713, v0
	v_mul_f32_e32 v1, v0, v1
	v_fma_f32 v1, v0, v1, v0
	v_mul_f32_e32 v1, 0x3f4c422a, v1
	v_add_f32_e32 v1, v1, v1
	v_mul_f32_e32 v1, 0x3fb8aa3b, v1
	v_exp_f32_e32 v1, v1
	v_mul_f32_e32 v0, 0.5, v0
	v_add_f32_e32 v1, 1.0, v1
	v_rcp_f32_e32 v1, v1
	s_nop 0
	v_fma_f32 v1, v1, -2.0, 1.0
	v_add_f32_e32 v1, 1.0, v1
	v_mul_f32_e32 v0, v0, v1
	v_cvt_pk_bf16_f32 v0, v0, s0
	ds_write_b16 v4, v0 offset:4624
	v_add_f32_e32 v0, v2, v11
	v_mul_f32_e32 v1, 0x3d372713, v0
	v_mul_f32_e32 v1, v0, v1
	v_fma_f32 v1, v0, v1, v0
	v_mul_f32_e32 v1, 0x3f4c422a, v1
	v_add_f32_e32 v1, v1, v1
	v_mul_f32_e32 v1, 0x3fb8aa3b, v1
	v_exp_f32_e32 v1, v1
	v_mul_f32_e32 v0, 0.5, v0
	v_add_f32_e32 v1, 1.0, v1
	v_rcp_f32_e32 v1, v1
	s_nop 0
	v_fma_f32 v1, v1, -2.0, 1.0
	v_add_f32_e32 v1, 1.0, v1
	v_mul_f32_e32 v0, v0, v1
	v_cvt_pk_bf16_f32 v0, v0, s0
	ds_write_b16 v4, v0 offset:4896
	v_add_f32_e32 v0, v3, v11
	v_mul_f32_e32 v1, 0x3d372713, v0
	v_mul_f32_e32 v1, v0, v1
	v_fma_f32 v1, v0, v1, v0
	v_mul_f32_e32 v1, 0x3f4c422a, v1
	v_add_f32_e32 v1, v1, v1
	v_mul_f32_e32 v1, 0x3fb8aa3b, v1
	v_exp_f32_e32 v1, v1
	v_mul_f32_e32 v0, 0.5, v0
	v_add_f32_e32 v1, 1.0, v1
	v_rcp_f32_e32 v1, v1
	s_nop 0
	v_fma_f32 v1, v1, -2.0, 1.0
	v_add_f32_e32 v1, 1.0, v1
	v_mul_f32_e32 v0, v0, v1
	v_cvt_pk_bf16_f32 v0, v0, s0
	ds_write_b16 v4, v0 offset:5168
	v_ashrrev_i32_e32 v0, 4, v9
	v_and_b32_e32 v17, -16, v0
	v_or_b32_e32 v0, v17, v21
	v_mul_lo_u32 v1, v0, s6
	v_lshlrev_b32_e32 v0, 1, v8
	v_readlane_b32 s6, v245, 52
	v_add3_u32 v8, 0, v1, v0
	v_readlane_b32 s7, v245, 53
	s_add_u32 s4, s6, s4
	v_lshlrev_b32_e32 v1, 8, v21
	s_addc_u32 s5, s7, s5
	v_lshl_or_b32 v128, v16, 12, v1
	v_lshl_add_u64 v[2:3], s[4:5], 0, v[128:129]
	v_mov_b32_e32 v1, v129
	v_lshl_add_u64 v[14:15], v[2:3], 0, v[0:1]
	s_waitcnt lgkmcnt(0)
	s_barrier
	global_load_dwordx4 v[4:7], v[14:15], off
	global_load_dwordx4 v[10:13], v[14:15], off offset:64
	ds_read_b128 v[0:3], v8
	s_waitcnt vmcnt(1) lgkmcnt(0)
	v_mfma_f32_16x16x32_bf16 v[0:3], v[0:3], v[4:7], 0
	ds_read_b128 v[4:7], v8 offset:64
	s_movk_i32 s4, 0x100
	v_cmp_gt_i32_e32 vcc, s4, v9
	s_waitcnt vmcnt(0) lgkmcnt(0)
	v_mfma_f32_16x16x32_bf16 v[0:3], v[4:7], v[10:13], v[0:3]
	global_load_dwordx4 v[10:13], v[14:15], off offset:128
	ds_read_b128 v[4:7], v8 offset:128
	s_waitcnt vmcnt(0) lgkmcnt(0)
	v_mfma_f32_16x16x32_bf16 v[0:3], v[4:7], v[10:13], v[0:3]
	global_load_dwordx4 v[10:13], v[14:15], off offset:192
	ds_read_b128 v[4:7], v8 offset:192
	s_waitcnt vmcnt(0) lgkmcnt(0)
	v_mfma_f32_16x16x32_bf16 v[0:3], v[4:7], v[10:13], v[0:3]
	v_lshlrev_b32_e32 v4, 6, v16
	v_lshlrev_b32_e32 v5, 2, v21
	v_add3_u32 v4, 0, v4, v5
	v_lshlrev_b32_e32 v5, 10, v20
	v_lshlrev_b32_e32 v6, 8, v17
	v_add3_u32 v4, v4, v5, v6
	s_nop 1
	ds_write2st64_b32 v4, v0, v1 offset0:34 offset1:35
	ds_write2st64_b32 v4, v2, v3 offset0:36 offset1:37
	s_waitcnt lgkmcnt(0)
	s_barrier
	s_and_saveexec_b64 s[4:5], vcc
	s_cbranch_execz .LBB0_598
	v_lshlrev_b32_e32 v0, 3, v9
	v_ashrrev_i32_e32 v8, 3, v9
	v_and_b32_e32 v12, 56, v0
	v_lshlrev_b32_e32 v0, 8, v8
	v_lshlrev_b32_e32 v128, 2, v12
	v_add3_u32 v0, 0, v0, v128
	ds_read_b128 v[4:7], v0 offset:8704
	ds_read_b128 v[0:3], v0 offset:8720
	s_and_b32 s6, s11, 7
	v_lshl_add_u32 v8, s6, 5, v8
	s_mov_b64 s[6:7], -1
	s_and_b64 vcc, exec, s[2:3]
	s_cbranch_vccz .LBB0_608
	s_lshl_b32 s2, s13, 15
	v_readlane_b32 s3, v245, 54
	s_add_u32 s2, s3, s2
	v_readlane_b32 s3, v245, 55
	s_movk_i32 s6, 0xff
	v_lshl_add_u32 v10, v12, 8, v8
	s_addc_u32 s3, s3, 0
	s_waitcnt lgkmcnt(1)
	v_cvt_pk_bf16_f32 v9, v4, s0
	v_cmp_eq_u32_e32 vcc, s6, v8
	v_ashrrev_i32_e32 v11, 31, v10
	v_lshl_add_u64 v[10:11], v[10:11], 1, s[2:3]
	v_cndmask_b32_e64 v9, v9, 0, vcc
	global_store_short v[10:11], v9, off
	v_cvt_pk_bf16_f32 v9, v5, s0
	v_cndmask_b32_e64 v9, v9, 0, vcc
	global_store_short v[10:11], v9, off offset:512
	v_cvt_pk_bf16_f32 v9, v6, s0
	v_cndmask_b32_e64 v9, v9, 0, vcc
	global_store_short v[10:11], v9, off offset:1024
	v_cvt_pk_bf16_f32 v9, v7, s0
	v_cndmask_b32_e64 v9, v9, 0, vcc
	global_store_short v[10:11], v9, off offset:1536
	s_waitcnt lgkmcnt(0)
	v_cvt_pk_bf16_f32 v9, v0, s0
	v_cndmask_b32_e64 v9, v9, 0, vcc
	global_store_short v[10:11], v9, off offset:2048
	v_cvt_pk_bf16_f32 v9, v1, s0
	v_cndmask_b32_e64 v9, v9, 0, vcc
	global_store_short v[10:11], v9, off offset:2560
	v_cvt_pk_bf16_f32 v9, v2, s0
	v_cndmask_b32_e64 v9, v9, 0, vcc
	global_store_short v[10:11], v9, off offset:3072
	v_cvt_pk_bf16_f32 v9, v3, s0
	v_cndmask_b32_e64 v9, v9, 0, vcc
	global_store_short v[10:11], v9, off offset:3584
	s_mov_b64 s[6:7], 0
